# seeding + sharded counters extended to phases P0 and P1 (flag-controlled first fetch)
# baseline (speedup 1.0000x reference)
.LBB0_5:
	s_ashr_i32 s15, s14, 31
	s_lshl_b64 s[0:1], s[14:15], 2
	v_readlane_b32 s2, v253, 23
	s_add_u32 s2, s2, s0
	v_readlane_b32 s0, v253, 24
	s_addc_u32 s3, s0, s1
	v_writelane_b32 v254, s2, 43
	s_mov_b32 s0, s14
	s_mov_b32 s28, 0x18000
	v_writelane_b32 v254, s3, 44
	v_writelane_b32 v254, s0, 45
	s_mov_b64 s[4:5], -1
	s_mov_b64 s[2:3], 0
	v_writelane_b32 v254, s1, 46
	s_mov_b32 s98, 1
	s_nop 0
	v_writelane_b32 v255, s98, 14
	s_mul_hi_u32 s98, s14, 0x55555556
	s_mul_i32 s98, s98, 3
	s_sub_i32 s98, s14, s98
	v_readlane_b32 s99, v254, 20
	s_and_b32 s99, s99, 7
	s_lshl_b32 s98, s98, 3
	s_add_i32 s98, s98, s99
	s_lshl_b32 s98, s98, 7
	s_add_i32 s98, s98, 0x3000
	v_readlane_b32 s0, v253, 17
	v_readlane_b32 s1, v253, 18
	s_add_u32 s0, s0, s98
	s_addc_u32 s1, s1, 0
	s_nop 0
	v_writelane_b32 v254, s0, 43
	v_writelane_b32 v254, s1, 44
	v_readlane_b32 s99, v254, 20
	s_cmp_lg_u32 s99, 0
	s_cbranch_scc1 .Lsh_skip
	s_add_i32 s98, s14, 1
	s_mul_hi_u32 s99, s98, 0x55555556
	s_mul_i32 s99, s99, 3
	s_sub_i32 s98, s98, s99
	s_lshl_b32 s98, s98, 10
	s_add_i32 s98, s98, 0x3000
	v_readlane_b32 s0, v253, 17
	v_readlane_b32 s1, v253, 18
	s_add_u32 s0, s0, s98
	s_addc_u32 s1, s1, 0
	s_and_saveexec_b64 s[98:99], s[12:13]
	global_store_dword v131, v131, s[0:1] sc1
	global_store_dword v131, v131, s[0:1] offset:128 sc1
	global_store_dword v131, v131, s[0:1] offset:256 sc1
	global_store_dword v131, v131, s[0:1] offset:384 sc1
	global_store_dword v131, v131, s[0:1] offset:512 sc1
	global_store_dword v131, v131, s[0:1] offset:640 sc1
	global_store_dword v131, v131, s[0:1] offset:768 sc1
	global_store_dword v131, v131, s[0:1] offset:896 sc1
	s_or_b64 exec, exec, s[98:99]

.LBB0_20:
	s_barrier
	s_and_saveexec_b64 s[0:1], s[12:13]
	s_cbranch_execz .LBB0_24
	s_mov_b64 s[6:7], exec
	v_mbcnt_lo_u32_b32 v1, s6, 0
	v_mbcnt_hi_u32_b32 v1, s7, v1
	v_cmp_eq_u32_e32 vcc, 0, v1
	s_and_saveexec_b64 s[4:5], vcc
	s_cbranch_execz .LBB0_23
	s_bcnt1_i32_b64 s6, s[6:7]
	s_waitcnt vmcnt(0)
	v_mov_b32_e32 v2, s6
	v_readlane_b32 s6, v254, 43
	v_readlane_b32 s7, v254, 44
	s_nop 4
	v_readlane_b32 s98, v255, 14
	s_cmp_eq_u32 s98, 0
	s_cbranch_scc1 .Lsdp1_at
	v_readlane_b32 s98, v254, 20
	s_nop 1
	v_mov_b32_e32 v2, s98
	s_branch .Lsdp1_j
.Lsdp1_at:
	global_atomic_add v2, v131, v2, s[6:7] sc0
.Lsdp1_j:
.LBB0_23:
	s_or_b64 exec, exec, s[4:5]
	s_waitcnt vmcnt(0)
	v_readfirstlane_b32 s4, v2
	s_nop 1
	v_add_u32_e32 v1, s4, v1
	ds_write_b32 v161, v1
.LBB0_24:
	s_or_b64 exec, exec, s[0:1]
	s_waitcnt lgkmcnt(0)
	s_barrier
	ds_read_b32 v1, v161
	s_waitcnt lgkmcnt(0)
	v_readfirstlane_b32 s10, v1
	v_readlane_b32 s98, v255, 14
	s_cmp_eq_u32 s98, 0
	s_cbranch_scc0 .Lsdp1_first
	v_readlane_b32 s98, v255, 13
	s_lshl_b32 s10, s10, 3
	s_add_i32 s10, s10, s98
	v_readlane_b32 s98, v254, 20
	s_and_b32 s98, s98, 7
	s_add_i32 s10, s10, s98
.Lsdp1_first:
	s_mov_b32 s98, 0
	s_nop 0
	v_writelane_b32 v255, s98, 14
	s_cmpk_gt_i32 s10, 0x4bf
	s_cbranch_scc1 .LBB0_114
	s_cmpk_lt_i32 s10, 0x80
	s_mov_b64 s[0:1], -1
	s_cbranch_scc1 .LBB0_29
	v_readlane_b32 s6, v253, 25
	s_lshl_b32 s0, s10, 4
	s_mov_b32 s1, 0
	v_readlane_b32 s7, v253, 26
	s_movk_i32 s5, 0x4000
	s_movk_i32 s8, 0x1000
	s_mov_b32 s9, 0x800000

.LBB0_872:
	s_barrier
	s_and_saveexec_b64 s[0:1], s[12:13]
	s_cbranch_execz .LBB0_876
	s_mov_b64 s[4:5], exec
	v_mbcnt_lo_u32_b32 v1, s4, 0
	v_mbcnt_hi_u32_b32 v1, s5, v1
	v_cmp_eq_u32_e32 vcc, 0, v1
	s_and_saveexec_b64 s[2:3], vcc
	s_cbranch_execz .LBB0_875
	s_bcnt1_i32_b64 s4, s[4:5]
	s_waitcnt vmcnt(0)
	v_mov_b32_e32 v2, s4
	v_readlane_b32 s4, v254, 43
	v_readlane_b32 s5, v254, 44
	s_nop 4
	v_readlane_b32 s98, v255, 14
	s_cmp_eq_u32 s98, 0
	s_cbranch_scc1 .Lsdp0_at
	v_readlane_b32 s98, v254, 20
	s_nop 1
	v_mov_b32_e32 v2, s98
	s_branch .Lsdp0_j
.Lsdp0_at:
	global_atomic_add v2, v131, v2, s[4:5] sc0
.Lsdp0_j:
.LBB0_875:
	s_or_b64 exec, exec, s[2:3]
	s_waitcnt vmcnt(0)
	v_readfirstlane_b32 s2, v2
	s_nop 1
	v_add_u32_e32 v1, s2, v1
	ds_write_b32 v161, v1
.LBB0_876:
	s_or_b64 exec, exec, s[0:1]
	s_waitcnt lgkmcnt(0)
	s_barrier
	ds_read_b32 v1, v161
	s_waitcnt lgkmcnt(0)
	v_readfirstlane_b32 s18, v1
	v_readlane_b32 s98, v255, 14
	s_cmp_eq_u32 s98, 0
	s_cbranch_scc0 .Lsdp0_first
	v_readlane_b32 s98, v255, 13
	s_lshl_b32 s18, s18, 3
	s_add_i32 s18, s18, s98
	v_readlane_b32 s98, v254, 20
	s_and_b32 s98, s98, 7
	s_add_i32 s18, s18, s98
.Lsdp0_first:
	s_mov_b32 s98, 0
	s_nop 0
	v_writelane_b32 v255, s98, 14
	s_cmpk_gt_i32 s18, 0x3e0
	s_cbranch_scc1 .LBB0_858
	s_cmpk_gt_i32 s18, 0x5f
	s_mov_b64 s[0:1], -1
	s_cbranch_scc0 .LBB0_1071
	s_cmpk_gt_u32 s18, 0x11f
	s_cbranch_scc0 .LBB0_1058
	s_cmpk_lg_i32 s18, 0x120
	s_cbranch_scc0 .LBB0_1034
	s_add_i32 s2, s18, 0xfffffedf
	s_cmpk_gt_u32 s2, 0x1bf
	s_cbranch_scc0 .LBB0_886
	s_waitcnt vmcnt(0)
	v_mov_b32_e32 v10, v0
	s_movk_i32 s0, 0x80
	s_nop 0
	v_cmp_gt_i32_e32 vcc, s0, v10
	v_lshlrev_b32_e32 v1, 2, v10
	s_barrier
	s_and_saveexec_b64 s[0:1], vcc
	s_cbranch_execz .LBB0_883
	v_cvt_f32_i32_e32 v2, v10
	s_brev_b32 s3, 1
	v_add_f32_e32 v2, v2, v2
	v_mul_f32_e32 v2, 0x3c000000, v2
	v_mul_f32_e64 v4, |v2|, 0.5
	v_fract_f32_e32 v5, v4
	v_add_f32_e32 v5, v5, v5
	v_cmp_neq_f32_e32 vcc, s33, v4
	v_cmp_gt_f32_e64 s[4:5], |v2|, 1.0
	v_and_b32_e32 v3, 0x7fffffff, v2
	v_cndmask_b32_e32 v4, 0, v5, vcc
	v_cndmask_b32_e64 v4, |v2|, v4, s[4:5]
	v_add_f32_e32 v5, v4, v4
	v_rndne_f32_e32 v5, v5
	v_fmac_f32_e32 v4, -0.5, v5
	v_mul_f32_e32 v6, v4, v4
	v_fmamk_f32 v7, v6, 0x3e75aa41, v179
	v_fmaak_f32 v7, v6, v7, 0x40234736
	v_fmaak_f32 v7, v6, v7, 0xc0a55e0e
	v_mul_f32_e32 v8, v4, v6
	v_mul_f32_e32 v7, v8, v7
	v_cvt_i32_f32_e32 v5, v5
	v_fmac_f32_e32 v7, 0x40490fdb, v4
	v_fmamk_f32 v4, v6, 0x3d4be544, v196
	v_fmaak_f32 v4, v6, v4, 0xbfaad1da
	v_fmaak_f32 v4, v6, v4, 0x4081e0d3
	v_fmaak_f32 v4, v6, v4, 0xc09de9e6
	v_fma_f32 v4, v6, v4, 1.0
	v_lshlrev_b32_e32 v6, 30, v5
	v_and_b32_e32 v5, 1, v5
	v_cmp_eq_u32_e32 vcc, 0, v5
	v_xor_b32_e32 v3, v3, v2
	v_and_b32_e32 v8, 0x80000000, v6
	v_cndmask_b32_e32 v5, v4, v7, vcc
	v_xor_b32_e32 v3, v3, v5
	v_xor_b32_e32 v5, 0x80000000, v7
	v_cndmask_b32_e32 v4, v5, v4, vcc
	v_bitop3_b32 v4, v4, v6, s3 bitop3:0x78
	s_movk_i32 s3, 0x1f8
	v_xor_b32_e32 v3, v3, v8
	v_cmp_class_f32_e64 vcc, v2, s3
	s_nop 1
	v_cndmask_b32_e32 v2, v211, v4, vcc
	v_cndmask_b32_e32 v3, v211, v3, vcc
	ds_write2st64_b32 v1, v2, v3 offset1:2
